# v40 + down-proj K-loop: loop-invariant LDS read addresses kept in spare VGPRs, removing the four v_add_u32 that opened two load segments per iteration (start-of-segment VALU, guide 6.4)
# speedup vs baseline: 1.0031x; 1.0017x over previous
.LBB0_365:
	v_and_b32_e32 v219, 15, v210
	v_and_b32_e32 v2, 48, v210
	v_lshlrev_b32_e32 v3, 2, v210
	s_and_b32 s95, s12, 3
	s_lshl_b32 s21, s57, 13
	v_lshl_or_b32 v2, v219, 6, v2
	v_and_b32_e32 v3, 32, v3
	v_bitop3_b32 v4, v2, s21, v3 bitop3:0xde
	s_lshl_b32 s21, s95, 12
	v_bitop3_b32 v3, s21, v2, v3 bitop3:0xf6
	s_add_i32 s21, s9, 0x18000
	s_or_b32 s65, s8, 0x80
	s_mov_b32 m0, s21
	s_add_i32 s64, s9, 0x1a000
	s_waitcnt vmcnt(2)
	s_barrier
	buffer_load_dwordx4 v131, s[36:39], s65 offen lds
	s_mov_b32 m0, s64
	s_or_b32 s78, s17, 0x80
	buffer_load_dwordx4 v133, s[36:39], s65 offen lds
	s_add_i32 s65, s9, 0x8000
	s_mov_b32 m0, s65
	s_add_i32 s67, s9, 0xa000
	buffer_load_dwordx4 v130, s[40:43], s78 offen lds
	s_mov_b32 m0, s67
	v_mov_b32_e32 v2, 0
	buffer_load_dwordx4 v132, s[40:43], s78 offen lds
	s_add_i32 s78, s9, 0x1c000
	s_or_b32 s43, s79, 0x80
	s_mov_b32 m0, s78
	s_add_i32 s79, s9, 0x1e000
	buffer_load_dwordx4 v131, s[36:39], s43 offen lds
	s_mov_b32 m0, s79
	v_lshl_or_b32 v218, s57, 6, v219
	buffer_load_dwordx4 v133, s[36:39], s43 offen lds
	s_waitcnt vmcnt(6)
	s_add_i32 s80, s9, 0xc000
	s_add_i32 s88, s9, 0xe000
	s_mov_b32 s89, -2
	s_mov_b32 s90, 0x160080
	v_add_u32_e32 v134, 0, v3
	v_add_u32_e32 v135, 0, v4
	v_mov_b32_e32 v3, v2
	v_mov_b32_e32 v4, v2
	v_mov_b32_e32 v5, v2
	v_mov_b32_e32 v6, v2
	v_mov_b32_e32 v7, v2
	v_mov_b32_e32 v8, v2
	v_mov_b32_e32 v9, v2
	v_mov_b32_e32 v22, v2
	v_mov_b32_e32 v23, v2
	v_mov_b32_e32 v24, v2
	v_mov_b32_e32 v25, v2
	v_mov_b32_e32 v30, v2
	v_mov_b32_e32 v31, v2
	v_mov_b32_e32 v32, v2
	v_mov_b32_e32 v33, v2
	v_mov_b32_e32 v110, v2
	v_mov_b32_e32 v111, v2
	v_mov_b32_e32 v112, v2
	v_mov_b32_e32 v113, v2
	v_mov_b32_e32 v122, v2
	v_mov_b32_e32 v123, v2
	v_mov_b32_e32 v124, v2
	v_mov_b32_e32 v125, v2
	v_mov_b32_e32 v118, v2
	v_mov_b32_e32 v119, v2
	v_mov_b32_e32 v120, v2
	v_mov_b32_e32 v121, v2
	v_mov_b32_e32 v126, v2
	v_mov_b32_e32 v127, v2
	v_mov_b32_e32 v128, v2
	v_mov_b32_e32 v129, v2
	v_mov_b32_e32 v10, v2
	v_mov_b32_e32 v11, v2
	v_mov_b32_e32 v12, v2
	v_mov_b32_e32 v13, v2
	v_mov_b32_e32 v14, v2
	v_mov_b32_e32 v15, v2
	v_mov_b32_e32 v16, v2
	v_mov_b32_e32 v17, v2
	v_mov_b32_e32 v66, v2
	v_mov_b32_e32 v67, v2
	v_mov_b32_e32 v68, v2
	v_mov_b32_e32 v69, v2
	v_mov_b32_e32 v74, v2
	v_mov_b32_e32 v75, v2
	v_mov_b32_e32 v76, v2
	v_mov_b32_e32 v77, v2
	v_mov_b32_e32 v106, v2
	v_mov_b32_e32 v107, v2
	v_mov_b32_e32 v108, v2
	v_mov_b32_e32 v109, v2
	v_mov_b32_e32 v114, v2
	v_mov_b32_e32 v115, v2
	v_mov_b32_e32 v116, v2
	v_mov_b32_e32 v117, v2
	v_mov_b32_e32 v90, v2
	v_mov_b32_e32 v91, v2
	v_mov_b32_e32 v92, v2
	v_mov_b32_e32 v93, v2
	v_mov_b32_e32 v94, v2
	v_mov_b32_e32 v95, v2
	v_mov_b32_e32 v96, v2
	v_mov_b32_e32 v97, v2
	v_mov_b32_e32 v98, v2
	v_mov_b32_e32 v99, v2
	v_mov_b32_e32 v100, v2
	v_mov_b32_e32 v101, v2
	v_mov_b32_e32 v102, v2
	v_mov_b32_e32 v103, v2
	v_mov_b32_e32 v104, v2
	v_mov_b32_e32 v105, v2
	v_mov_b32_e32 v82, v2
	v_mov_b32_e32 v83, v2
	v_mov_b32_e32 v84, v2
	v_mov_b32_e32 v85, v2
	v_mov_b32_e32 v86, v2
	v_mov_b32_e32 v87, v2
	v_mov_b32_e32 v88, v2
	v_mov_b32_e32 v89, v2
	v_mov_b32_e32 v58, v2
	v_mov_b32_e32 v59, v2
	v_mov_b32_e32 v60, v2
	v_mov_b32_e32 v61, v2
	v_mov_b32_e32 v62, v2
	v_mov_b32_e32 v63, v2
	v_mov_b32_e32 v64, v2
	v_mov_b32_e32 v65, v2
	v_mov_b32_e32 v38, v2
	v_mov_b32_e32 v39, v2
	v_mov_b32_e32 v40, v2
	v_mov_b32_e32 v41, v2
	v_mov_b32_e32 v46, v2
	v_mov_b32_e32 v47, v2
	v_mov_b32_e32 v48, v2
	v_mov_b32_e32 v49, v2
	v_mov_b32_e32 v70, v2
	v_mov_b32_e32 v71, v2
	v_mov_b32_e32 v72, v2
	v_mov_b32_e32 v73, v2
	v_mov_b32_e32 v78, v2
	v_mov_b32_e32 v79, v2
	v_mov_b32_e32 v80, v2
	v_mov_b32_e32 v81, v2
	v_mov_b32_e32 v50, v2
	v_mov_b32_e32 v51, v2
	v_mov_b32_e32 v52, v2
	v_mov_b32_e32 v53, v2
	v_mov_b32_e32 v54, v2
	v_mov_b32_e32 v55, v2
	v_mov_b32_e32 v56, v2
	v_mov_b32_e32 v57, v2
	v_mov_b32_e32 v34, v2
	v_mov_b32_e32 v35, v2
	v_mov_b32_e32 v36, v2
	v_mov_b32_e32 v37, v2
	v_mov_b32_e32 v42, v2
	v_mov_b32_e32 v43, v2
	v_mov_b32_e32 v44, v2
	v_mov_b32_e32 v45, v2
	v_mov_b32_e32 v18, v2
	v_mov_b32_e32 v19, v2
	v_mov_b32_e32 v20, v2
	v_mov_b32_e32 v21, v2
	v_mov_b32_e32 v26, v2
	v_mov_b32_e32 v27, v2
	v_mov_b32_e32 v28, v2
	v_mov_b32_e32 v29, v2
	v_add_u32_e32 v203, 0x10000, v134
	v_add_u32_e32 v204, 0x14000, v134
	v_add_u32_e32 v205, 0x18000, v134
	v_add_u32_e32 v206, 0x1c000, v134
	s_barrier
.LBB0_366:
	ds_read_b128 v[136:139], v203
	ds_read_b128 v[140:143], v203 offset:1024
	ds_read_b128 v[144:147], v203 offset:2048
	ds_read_b128 v[148:151], v203 offset:3072
	ds_read_b128 v[152:155], v204
	ds_read_b128 v[156:159], v204 offset:1024
	ds_read_b128 v[160:163], v204 offset:2048
	ds_read_b128 v[164:167], v204 offset:3072
	s_add_i32 s39, s90, 0xffea0080
	s_cmpk_lg_i32 s89, 0x54
	s_cselect_b32 vcc_lo, s39, 0
	s_add_i32 vcc_hi, vcc_lo, s17
	s_or_b32 s91, vcc_hi, 0x80
	s_add_i32 s93, vcc_lo, s8
	s_add_i32 s39, s17, s90
	s_mov_b32 s43, s31
	s_mov_b32 m0, s80
	ds_read_b128 v[168:171], v135
	ds_read_b128 v[172:175], v135 offset:1024
	ds_read_b128 v[176:179], v135 offset:2048
	ds_read_b128 v[180:183], v135 offset:3072
	ds_read_b128 v[184:187], v135 offset:4096
	ds_read_b128 v[188:191], v135 offset:5120
	ds_read_b128 v[192:195], v135 offset:6144
	ds_read_b128 v[196:199], v135 offset:7168
	buffer_load_dwordx4 v130, s[40:43], s39 offen lds
	s_mov_b32 m0, s88
	s_nop 0
	buffer_load_dwordx4 v132, s[40:43], s39 offen lds
	s_waitcnt vmcnt(8)
	s_waitcnt lgkmcnt(0)
	s_barrier
	s_setprio 1
	s_waitcnt lgkmcnt(7)
	v_mfma_f32_16x16x32_bf16 v[26:29], v[136:139], v[168:171], v[26:29]
	v_mfma_f32_16x16x32_bf16 v[18:21], v[144:147], v[168:171], v[18:21]
	s_waitcnt lgkmcnt(5)
	v_mfma_f32_16x16x32_bf16 v[42:45], v[136:139], v[176:179], v[42:45]
	v_mfma_f32_16x16x32_bf16 v[34:37], v[144:147], v[176:179], v[34:37]
	s_waitcnt lgkmcnt(3)
	v_mfma_f32_16x16x32_bf16 v[54:57], v[136:139], v[184:187], v[54:57]
	v_mfma_f32_16x16x32_bf16 v[50:53], v[144:147], v[184:187], v[50:53]
	s_waitcnt lgkmcnt(1)
	v_mfma_f32_16x16x32_bf16 v[78:81], v[136:139], v[192:195], v[78:81]
	v_mfma_f32_16x16x32_bf16 v[70:73], v[144:147], v[192:195], v[70:73]
	v_mfma_f32_16x16x32_bf16 v[26:29], v[140:143], v[172:175], v[26:29]
	v_mfma_f32_16x16x32_bf16 v[18:21], v[148:151], v[172:175], v[18:21]
	v_mfma_f32_16x16x32_bf16 v[42:45], v[140:143], v[180:183], v[42:45]
	v_mfma_f32_16x16x32_bf16 v[34:37], v[148:151], v[180:183], v[34:37]
	v_mfma_f32_16x16x32_bf16 v[54:57], v[140:143], v[188:191], v[54:57]
	v_mfma_f32_16x16x32_bf16 v[50:53], v[148:151], v[188:191], v[50:53]
	s_waitcnt lgkmcnt(0)
	v_mfma_f32_16x16x32_bf16 v[78:81], v[140:143], v[196:199], v[78:81]
	v_mfma_f32_16x16x32_bf16 v[70:73], v[148:151], v[196:199], v[70:73]
	s_setprio 0
	s_setprio 1
	v_mfma_f32_16x16x32_bf16 v[46:49], v[152:155], v[168:171], v[46:49]
	v_mfma_f32_16x16x32_bf16 v[38:41], v[160:163], v[168:171], v[38:41]
	v_mfma_f32_16x16x32_bf16 v[62:65], v[152:155], v[176:179], v[62:65]
	v_mfma_f32_16x16x32_bf16 v[58:61], v[160:163], v[176:179], v[58:61]
	v_mfma_f32_16x16x32_bf16 v[86:89], v[152:155], v[184:187], v[86:89]
	v_mfma_f32_16x16x32_bf16 v[82:85], v[160:163], v[184:187], v[82:85]
	v_mfma_f32_16x16x32_bf16 v[102:105], v[152:155], v[192:195], v[102:105]
	v_mfma_f32_16x16x32_bf16 v[98:101], v[160:163], v[192:195], v[98:101]
	v_mfma_f32_16x16x32_bf16 v[46:49], v[156:159], v[172:175], v[46:49]
	v_mfma_f32_16x16x32_bf16 v[38:41], v[164:167], v[172:175], v[38:41]
	v_mfma_f32_16x16x32_bf16 v[62:65], v[156:159], v[180:183], v[62:65]
	v_mfma_f32_16x16x32_bf16 v[58:61], v[164:167], v[180:183], v[58:61]
	v_mfma_f32_16x16x32_bf16 v[86:89], v[156:159], v[188:191], v[86:89]
	v_mfma_f32_16x16x32_bf16 v[82:85], v[164:167], v[188:191], v[82:85]
	v_mfma_f32_16x16x32_bf16 v[102:105], v[156:159], v[196:199], v[102:105]
	v_mfma_f32_16x16x32_bf16 v[98:101], v[164:167], v[196:199], v[98:101]
	s_setprio 0
	s_barrier
	s_mov_b32 m0, s10
	s_mov_b32 s39, s31
	ds_read_b128 v[168:171], v135 offset:16384
	ds_read_b128 v[172:175], v135 offset:17408
	ds_read_b128 v[176:179], v135 offset:18432
	ds_read_b128 v[180:183], v135 offset:19456
	ds_read_b128 v[184:187], v135 offset:20480
	ds_read_b128 v[188:191], v135 offset:21504
	ds_read_b128 v[192:195], v135 offset:22528
	ds_read_b128 v[196:199], v135 offset:23552
	buffer_load_dwordx4 v131, s[36:39], s93 offen lds
	s_mov_b32 m0, s11
	s_add_i32 vcc_lo, s93, 0x160000
	buffer_load_dwordx4 v133, s[36:39], s93 offen lds
	s_mov_b32 m0, s15
	s_nop 0
	buffer_load_dwordx4 v131, s[36:39], vcc_lo offen lds
	s_mov_b32 m0, s16
	s_nop 0
	buffer_load_dwordx4 v133, s[36:39], vcc_lo offen lds
	s_mov_b32 m0, s9
	s_nop 0
	buffer_load_dwordx4 v130, s[40:43], vcc_hi offen lds
	s_mov_b32 m0, s18
	s_nop 0
	buffer_load_dwordx4 v132, s[40:43], vcc_hi offen lds
	s_waitcnt vmcnt(8)
	s_waitcnt lgkmcnt(0)
	s_barrier
	s_setprio 1
	s_waitcnt lgkmcnt(7)
	v_mfma_f32_16x16x32_bf16 v[94:97], v[136:139], v[168:171], v[94:97]
	v_mfma_f32_16x16x32_bf16 v[90:93], v[144:147], v[168:171], v[90:93]
	s_waitcnt lgkmcnt(5)
	v_mfma_f32_16x16x32_bf16 v[114:117], v[136:139], v[176:179], v[114:117]
	v_mfma_f32_16x16x32_bf16 v[106:109], v[144:147], v[176:179], v[106:109]
	s_waitcnt lgkmcnt(3)
	v_mfma_f32_16x16x32_bf16 v[74:77], v[136:139], v[184:187], v[74:77]
	v_mfma_f32_16x16x32_bf16 v[66:69], v[144:147], v[184:187], v[66:69]
	s_waitcnt lgkmcnt(1)
	v_mfma_f32_16x16x32_bf16 v[14:17], v[136:139], v[192:195], v[14:17]
	v_mfma_f32_16x16x32_bf16 v[10:13], v[144:147], v[192:195], v[10:13]
	v_mfma_f32_16x16x32_bf16 v[94:97], v[140:143], v[172:175], v[94:97]
	v_mfma_f32_16x16x32_bf16 v[90:93], v[148:151], v[172:175], v[90:93]
	v_mfma_f32_16x16x32_bf16 v[114:117], v[140:143], v[180:183], v[114:117]
	v_mfma_f32_16x16x32_bf16 v[106:109], v[148:151], v[180:183], v[106:109]
	v_mfma_f32_16x16x32_bf16 v[74:77], v[140:143], v[188:191], v[74:77]
	v_mfma_f32_16x16x32_bf16 v[66:69], v[148:151], v[188:191], v[66:69]
	s_waitcnt lgkmcnt(0)
	v_mfma_f32_16x16x32_bf16 v[14:17], v[140:143], v[196:199], v[14:17]
	v_mfma_f32_16x16x32_bf16 v[10:13], v[148:151], v[196:199], v[10:13]
	s_setprio 0
	s_setprio 1
	v_mfma_f32_16x16x32_bf16 v[126:129], v[152:155], v[168:171], v[126:129]
	v_mfma_f32_16x16x32_bf16 v[118:121], v[160:163], v[168:171], v[118:121]
	v_mfma_f32_16x16x32_bf16 v[122:125], v[152:155], v[176:179], v[122:125]
	v_mfma_f32_16x16x32_bf16 v[110:113], v[160:163], v[176:179], v[110:113]
	v_mfma_f32_16x16x32_bf16 v[30:33], v[152:155], v[184:187], v[30:33]
	v_mfma_f32_16x16x32_bf16 v[22:25], v[160:163], v[184:187], v[22:25]
	v_mfma_f32_16x16x32_bf16 v[6:9], v[152:155], v[192:195], v[6:9]
	v_mfma_f32_16x16x32_bf16 v[2:5], v[160:163], v[192:195], v[2:5]
	v_mfma_f32_16x16x32_bf16 v[126:129], v[156:159], v[172:175], v[126:129]
	v_mfma_f32_16x16x32_bf16 v[118:121], v[164:167], v[172:175], v[118:121]
	v_mfma_f32_16x16x32_bf16 v[122:125], v[156:159], v[180:183], v[122:125]
	v_mfma_f32_16x16x32_bf16 v[110:113], v[164:167], v[180:183], v[110:113]
	v_mfma_f32_16x16x32_bf16 v[30:33], v[156:159], v[188:191], v[30:33]
	v_mfma_f32_16x16x32_bf16 v[22:25], v[164:167], v[188:191], v[22:25]
	v_mfma_f32_16x16x32_bf16 v[6:9], v[156:159], v[196:199], v[6:9]
	v_mfma_f32_16x16x32_bf16 v[2:5], v[164:167], v[196:199], v[2:5]
	s_setprio 0
	s_barrier
	ds_read_b128 v[136:139], v205
	ds_read_b128 v[140:143], v205 offset:1024
	ds_read_b128 v[144:147], v205 offset:2048
	ds_read_b128 v[148:151], v205 offset:3072
	ds_read_b128 v[152:155], v206
	ds_read_b128 v[156:159], v206 offset:1024
	ds_read_b128 v[160:163], v206 offset:2048
	ds_read_b128 v[164:167], v206 offset:3072
	s_add_i32 vcc_hi, vcc_hi, 0x160000
	s_mov_b32 m0, s19
	ds_read_b128 v[168:171], v135 offset:32768
	ds_read_b128 v[172:175], v135 offset:33792
	ds_read_b128 v[176:179], v135 offset:34816
	ds_read_b128 v[180:183], v135 offset:35840
	ds_read_b128 v[184:187], v135 offset:36864
	ds_read_b128 v[188:191], v135 offset:37888
	ds_read_b128 v[192:195], v135 offset:38912
	ds_read_b128 v[196:199], v135 offset:39936
	buffer_load_dwordx4 v130, s[40:43], vcc_hi offen lds
	s_mov_b32 m0, s20
	s_nop 0
	buffer_load_dwordx4 v132, s[40:43], vcc_hi offen lds
	s_waitcnt vmcnt(8)
	s_waitcnt lgkmcnt(0)
	s_barrier
	s_setprio 1
	s_waitcnt lgkmcnt(7)
	v_mfma_f32_16x16x32_bf16 v[26:29], v[136:139], v[168:171], v[26:29]
	v_mfma_f32_16x16x32_bf16 v[18:21], v[144:147], v[168:171], v[18:21]
	s_waitcnt lgkmcnt(5)
	v_mfma_f32_16x16x32_bf16 v[42:45], v[136:139], v[176:179], v[42:45]
	v_mfma_f32_16x16x32_bf16 v[34:37], v[144:147], v[176:179], v[34:37]
	s_waitcnt lgkmcnt(3)
	v_mfma_f32_16x16x32_bf16 v[54:57], v[136:139], v[184:187], v[54:57]
	v_mfma_f32_16x16x32_bf16 v[50:53], v[144:147], v[184:187], v[50:53]
	s_waitcnt lgkmcnt(1)
	v_mfma_f32_16x16x32_bf16 v[78:81], v[136:139], v[192:195], v[78:81]
	v_mfma_f32_16x16x32_bf16 v[70:73], v[144:147], v[192:195], v[70:73]
	v_mfma_f32_16x16x32_bf16 v[26:29], v[140:143], v[172:175], v[26:29]
	v_mfma_f32_16x16x32_bf16 v[18:21], v[148:151], v[172:175], v[18:21]
	v_mfma_f32_16x16x32_bf16 v[42:45], v[140:143], v[180:183], v[42:45]
	v_mfma_f32_16x16x32_bf16 v[34:37], v[148:151], v[180:183], v[34:37]
	v_mfma_f32_16x16x32_bf16 v[54:57], v[140:143], v[188:191], v[54:57]
	v_mfma_f32_16x16x32_bf16 v[50:53], v[148:151], v[188:191], v[50:53]
	s_waitcnt lgkmcnt(0)
	v_mfma_f32_16x16x32_bf16 v[78:81], v[140:143], v[196:199], v[78:81]
	v_mfma_f32_16x16x32_bf16 v[70:73], v[148:151], v[196:199], v[70:73]
	s_setprio 0
	s_setprio 1
	v_mfma_f32_16x16x32_bf16 v[46:49], v[152:155], v[168:171], v[46:49]
	v_mfma_f32_16x16x32_bf16 v[38:41], v[160:163], v[168:171], v[38:41]
	v_mfma_f32_16x16x32_bf16 v[62:65], v[152:155], v[176:179], v[62:65]
	v_mfma_f32_16x16x32_bf16 v[58:61], v[160:163], v[176:179], v[58:61]
	v_mfma_f32_16x16x32_bf16 v[86:89], v[152:155], v[184:187], v[86:89]
	v_mfma_f32_16x16x32_bf16 v[82:85], v[160:163], v[184:187], v[82:85]
	v_mfma_f32_16x16x32_bf16 v[102:105], v[152:155], v[192:195], v[102:105]
	v_mfma_f32_16x16x32_bf16 v[98:101], v[160:163], v[192:195], v[98:101]
	v_mfma_f32_16x16x32_bf16 v[46:49], v[156:159], v[172:175], v[46:49]
	v_mfma_f32_16x16x32_bf16 v[38:41], v[164:167], v[172:175], v[38:41]
	v_mfma_f32_16x16x32_bf16 v[62:65], v[156:159], v[180:183], v[62:65]
	v_mfma_f32_16x16x32_bf16 v[58:61], v[164:167], v[180:183], v[58:61]
	v_mfma_f32_16x16x32_bf16 v[86:89], v[156:159], v[188:191], v[86:89]
	v_mfma_f32_16x16x32_bf16 v[82:85], v[164:167], v[188:191], v[82:85]
	v_mfma_f32_16x16x32_bf16 v[102:105], v[156:159], v[196:199], v[102:105]
	v_mfma_f32_16x16x32_bf16 v[98:101], v[164:167], v[196:199], v[98:101]
	s_setprio 0
	s_barrier
	s_mov_b32 m0, s21
	s_or_b32 vcc_lo, s93, 0x80
	ds_read_b128 v[168:171], v135 offset:49152
	ds_read_b128 v[172:175], v135 offset:50176
	ds_read_b128 v[176:179], v135 offset:51200
	ds_read_b128 v[180:183], v135 offset:52224
	ds_read_b128 v[184:187], v135 offset:53248
	ds_read_b128 v[188:191], v135 offset:54272
	ds_read_b128 v[192:195], v135 offset:55296
	ds_read_b128 v[196:199], v135 offset:56320
	buffer_load_dwordx4 v131, s[36:39], vcc_lo offen lds
	s_mov_b32 m0, s64
	s_add_i32 s93, s93, 0x160080
	buffer_load_dwordx4 v133, s[36:39], vcc_lo offen lds
	s_mov_b32 m0, s78
	s_nop 0
	buffer_load_dwordx4 v131, s[36:39], s93 offen lds
	s_mov_b32 m0, s79
	s_nop 0
	buffer_load_dwordx4 v133, s[36:39], s93 offen lds
	s_mov_b32 m0, s65
	s_nop 0
	buffer_load_dwordx4 v130, s[40:43], s91 offen lds
	s_mov_b32 m0, s67
	s_nop 0
	buffer_load_dwordx4 v132, s[40:43], s91 offen lds
	s_waitcnt vmcnt(8)
	s_waitcnt lgkmcnt(0)
	s_barrier
	s_setprio 1
	s_waitcnt lgkmcnt(7)
	v_mfma_f32_16x16x32_bf16 v[94:97], v[136:139], v[168:171], v[94:97]
	v_mfma_f32_16x16x32_bf16 v[90:93], v[144:147], v[168:171], v[90:93]
	s_waitcnt lgkmcnt(5)
	v_mfma_f32_16x16x32_bf16 v[114:117], v[136:139], v[176:179], v[114:117]
	v_mfma_f32_16x16x32_bf16 v[106:109], v[144:147], v[176:179], v[106:109]
	s_waitcnt lgkmcnt(3)
	v_mfma_f32_16x16x32_bf16 v[74:77], v[136:139], v[184:187], v[74:77]
	v_mfma_f32_16x16x32_bf16 v[66:69], v[144:147], v[184:187], v[66:69]
	s_waitcnt lgkmcnt(1)
	v_mfma_f32_16x16x32_bf16 v[14:17], v[136:139], v[192:195], v[14:17]
	v_mfma_f32_16x16x32_bf16 v[10:13], v[144:147], v[192:195], v[10:13]
	v_mfma_f32_16x16x32_bf16 v[94:97], v[140:143], v[172:175], v[94:97]
	v_mfma_f32_16x16x32_bf16 v[90:93], v[148:151], v[172:175], v[90:93]
	v_mfma_f32_16x16x32_bf16 v[114:117], v[140:143], v[180:183], v[114:117]
	v_mfma_f32_16x16x32_bf16 v[106:109], v[148:151], v[180:183], v[106:109]
	v_mfma_f32_16x16x32_bf16 v[74:77], v[140:143], v[188:191], v[74:77]
	v_mfma_f32_16x16x32_bf16 v[66:69], v[148:151], v[188:191], v[66:69]
	s_waitcnt lgkmcnt(0)
	v_mfma_f32_16x16x32_bf16 v[14:17], v[140:143], v[196:199], v[14:17]
	v_mfma_f32_16x16x32_bf16 v[10:13], v[148:151], v[196:199], v[10:13]
	s_setprio 0
	s_setprio 1
	v_mfma_f32_16x16x32_bf16 v[126:129], v[152:155], v[168:171], v[126:129]
	v_mfma_f32_16x16x32_bf16 v[118:121], v[160:163], v[168:171], v[118:121]
	v_mfma_f32_16x16x32_bf16 v[122:125], v[152:155], v[176:179], v[122:125]
	v_mfma_f32_16x16x32_bf16 v[110:113], v[160:163], v[176:179], v[110:113]
	v_mfma_f32_16x16x32_bf16 v[30:33], v[152:155], v[184:187], v[30:33]
	v_mfma_f32_16x16x32_bf16 v[22:25], v[160:163], v[184:187], v[22:25]
	v_mfma_f32_16x16x32_bf16 v[6:9], v[152:155], v[192:195], v[6:9]
	v_mfma_f32_16x16x32_bf16 v[2:5], v[160:163], v[192:195], v[2:5]
	v_mfma_f32_16x16x32_bf16 v[126:129], v[156:159], v[172:175], v[126:129]
	v_mfma_f32_16x16x32_bf16 v[118:121], v[164:167], v[172:175], v[118:121]
	v_mfma_f32_16x16x32_bf16 v[122:125], v[156:159], v[180:183], v[122:125]
	v_mfma_f32_16x16x32_bf16 v[110:113], v[164:167], v[180:183], v[110:113]
	v_mfma_f32_16x16x32_bf16 v[30:33], v[156:159], v[188:191], v[30:33]
	v_mfma_f32_16x16x32_bf16 v[22:25], v[164:167], v[188:191], v[22:25]
	v_mfma_f32_16x16x32_bf16 v[6:9], v[156:159], v[196:199], v[6:9]
	v_mfma_f32_16x16x32_bf16 v[2:5], v[164:167], v[196:199], v[2:5]
	s_setprio 0
	s_barrier
	s_add_i32 s89, s89, 2
	s_addk_i32 s90, 0x100
	s_cmpk_lt_u32 s89, 0x56
	s_cbranch_scc1 .LBB0_366
	s_waitcnt vmcnt(0)
	s_cmpk_gt_u32 s66, 0xff
	s_cbranch_scc1 .LBB0_369
	s_barrier
